# v31 + nt hint on the UP GEMM (SwiGLU) output stores
# baseline (speedup 1.0000x reference)
; DI unsigned pk2(float lo, float hi) { f32x2 v = {lo, hi}; bf16x2_t b = __builtin_convertvector(v, bf16x2_t); return __builtin_bit_cast(unsigned, b); }
; DI float silu_f(float x) { return x * __builtin_amdgcn_rcpf(1.f + __expf(-x)); }
;     DI void operator()(const pg8::f32x4 (&acc)[2][2][4][2], const pg8::Unit& u, int wr, int wc, int fr, int fq) const {
;     ...
;         for (int ai = 0; ai < 2; ++ai)
; #pragma unroll
;             for (int m = 0; m < 4; ++m) {
;                 bf16* p = H + (size_t)(row0 + ai * 128 + m * 16) * DFF + col;
;                 float h[8];
; #pragma unroll
;                 for (int n = 0; n < 2; ++n)
; #pragma unroll
;                     for (int j = 0; j < 4; ++j) h[n * 4 + j] = silu_f(acc[ai][0][m][n][j]) * acc[ai][1][m][n][j];
;                 u32x4 w; w.x = pk2(h[0], h[1]); w.y = pk2(h[2], h[3]); w.z = pk2(h[4], h[5]); w.w = pk2(h[6], h[7]);
;                 *(u32x4*)p = w;
;                 __builtin_amdgcn_sched_barrier(0);
.LBB0_924:
	v_mul_f32_e32 v138, 0xbfb8aa3b, v124
	v_exp_f32_e32 v138, v138
	v_mul_f32_e32 v139, 0xbfb8aa3b, v125
	v_exp_f32_e32 v139, v139
	v_mul_f32_e32 v150, 0xbfb8aa3b, v126
	v_add_f32_e32 v138, 1.0, v138
	v_rcp_f32_e32 v156, v138
	v_add_f32_e32 v138, 1.0, v139
	v_rcp_f32_e32 v157, v138
	v_mul_f32_e32 v151, 0xbfb8aa3b, v127
	v_exp_f32_e32 v150, v150
	v_exp_f32_e32 v151, v151
	v_pk_mul_f32 v[124:125], v[124:125], v[156:157]
	v_lshl_or_b32 v154, s37, 7, v142
	v_pk_mul_f32 v[116:117], v[124:125], v[116:117]
	v_add_f32_e32 v124, 1.0, v150
	v_add_f32_e32 v125, 1.0, v151
	v_mul_f32_e32 v150, 0xbfb8aa3b, v120
	v_rcp_f32_e32 v124, v124
	v_rcp_f32_e32 v125, v125
	v_exp_f32_e32 v150, v150
	v_mul_f32_e32 v151, 0xbfb8aa3b, v121
	v_exp_f32_e32 v151, v151
	v_pk_mul_f32 v[124:125], v[126:127], v[124:125]
	v_add_f32_e32 v126, 1.0, v150
	v_mul_f32_e32 v150, 0xbfb8aa3b, v122
	v_add_f32_e32 v127, 1.0, v151
	v_exp_f32_e32 v150, v150
	v_mul_f32_e32 v151, 0xbfb8aa3b, v123
	v_exp_f32_e32 v151, v151
	v_rcp_f32_e32 v126, v126
	v_add_f32_e32 v150, 1.0, v150
	v_rcp_f32_e32 v127, v127
	v_rcp_f32_e32 v156, v150
	v_add_f32_e32 v150, 1.0, v151
	v_rcp_f32_e32 v157, v150
	v_pk_mul_f32 v[120:121], v[120:121], v[126:127]
	v_lshl_add_u32 v153, s14, 8, v140
	v_ashrrev_i32_e32 v155, 31, v154
	v_mov_b64_e32 v[138:139], s[74:75]
	s_movk_i32 s7, 0x1600
	v_pk_mul_f32 v[120:121], v[120:121], v[112:113]
	v_pk_mul_f32 v[112:113], v[122:123], v[156:157]
	v_mad_i64_i32 v[158:159], s[16:17], v153, s7, v[138:139]
	v_pk_mul_f32 v[118:119], v[124:125], v[118:119]
	v_pk_mul_f32 v[122:123], v[112:113], v[114:115]
	v_lshlrev_b64 v[112:113], 1, v[154:155]
	v_lshl_add_u64 v[124:125], v[158:159], 0, v[112:113]
	v_cvt_pk_bf16_f32 v114, v116, v117
	v_cvt_pk_bf16_f32 v115, v118, v119
	v_cvt_pk_bf16_f32 v116, v120, v121
	v_cvt_pk_bf16_f32 v117, v122, v123
	global_store_dwordx4 v[124:125], v[114:117], off nt
	s_nop 1
	v_mul_f32_e32 v114, 0xbfb8aa3b, v108
	v_mul_f32_e32 v115, 0xbfb8aa3b, v109
	v_exp_f32_e32 v114, v114
	v_exp_f32_e32 v115, v115
	v_or_b32_e32 v116, 16, v153
	v_mad_i64_i32 v[116:117], s[16:17], v116, s7, v[138:139]
	v_add_f32_e32 v114, 1.0, v114
	v_add_f32_e32 v115, 1.0, v115
	v_rcp_f32_e32 v114, v114
	v_rcp_f32_e32 v115, v115
	s_nop 0
	v_pk_mul_f32 v[108:109], v[108:109], v[114:115]
	v_mul_f32_e32 v114, 0xbfb8aa3b, v110
	v_mul_f32_e32 v115, 0xbfb8aa3b, v111
	v_exp_f32_e32 v114, v114
	v_exp_f32_e32 v115, v115
	v_pk_mul_f32 v[100:101], v[108:109], v[100:101]
	v_add_f32_e32 v108, 1.0, v114
	v_add_f32_e32 v109, 1.0, v115
	v_mul_f32_e32 v114, 0xbfb8aa3b, v104
	v_mul_f32_e32 v115, 0xbfb8aa3b, v105
	v_rcp_f32_e32 v108, v108
	v_rcp_f32_e32 v109, v109
	v_exp_f32_e32 v114, v114
	v_exp_f32_e32 v115, v115
	v_pk_mul_f32 v[108:109], v[110:111], v[108:109]
	v_add_f32_e32 v110, 1.0, v114
	v_add_f32_e32 v111, 1.0, v115
	v_mul_f32_e32 v114, 0xbfb8aa3b, v106
	v_mul_f32_e32 v115, 0xbfb8aa3b, v107
	v_exp_f32_e32 v114, v114
	v_exp_f32_e32 v115, v115
	v_rcp_f32_e32 v110, v110
	v_rcp_f32_e32 v111, v111
	v_add_f32_e32 v114, 1.0, v114
	v_add_f32_e32 v115, 1.0, v115
	v_rcp_f32_e32 v114, v114
	v_rcp_f32_e32 v115, v115
	v_pk_mul_f32 v[104:105], v[104:105], v[110:111]
	v_pk_mul_f32 v[102:103], v[108:109], v[102:103]
	v_pk_mul_f32 v[104:105], v[104:105], v[96:97]
	v_pk_mul_f32 v[96:97], v[106:107], v[114:115]
	v_lshl_add_u64 v[108:109], v[116:117], 0, v[112:113]
	v_pk_mul_f32 v[106:107], v[96:97], v[98:99]
	v_cvt_pk_bf16_f32 v96, v100, v101
	v_cvt_pk_bf16_f32 v97, v102, v103
	v_cvt_pk_bf16_f32 v98, v104, v105
	v_cvt_pk_bf16_f32 v99, v106, v107
	global_store_dwordx4 v[108:109], v[96:99], off nt
	s_nop 1
	v_mul_f32_e32 v96, 0xbfb8aa3b, v92
	v_mul_f32_e32 v97, 0xbfb8aa3b, v93
	v_exp_f32_e32 v96, v96
	v_exp_f32_e32 v97, v97
	v_or_b32_e32 v98, 32, v153
	v_mad_i64_i32 v[98:99], s[16:17], v98, s7, v[138:139]
	v_add_f32_e32 v96, 1.0, v96
	v_add_f32_e32 v97, 1.0, v97
	v_rcp_f32_e32 v96, v96
	v_rcp_f32_e32 v97, v97
	s_nop 0
	v_pk_mul_f32 v[92:93], v[92:93], v[96:97]
	v_mul_f32_e32 v96, 0xbfb8aa3b, v94
	v_mul_f32_e32 v97, 0xbfb8aa3b, v95
	v_exp_f32_e32 v96, v96
	v_exp_f32_e32 v97, v97
	v_pk_mul_f32 v[84:85], v[92:93], v[84:85]
	v_add_f32_e32 v92, 1.0, v96
	v_add_f32_e32 v93, 1.0, v97
	v_mul_f32_e32 v96, 0xbfb8aa3b, v88
	v_mul_f32_e32 v97, 0xbfb8aa3b, v89
	v_rcp_f32_e32 v92, v92
	v_rcp_f32_e32 v93, v93
	v_exp_f32_e32 v96, v96
	v_exp_f32_e32 v97, v97
	v_pk_mul_f32 v[92:93], v[94:95], v[92:93]
	v_add_f32_e32 v94, 1.0, v96
	v_add_f32_e32 v95, 1.0, v97
	v_mul_f32_e32 v96, 0xbfb8aa3b, v90
	v_mul_f32_e32 v97, 0xbfb8aa3b, v91
	v_exp_f32_e32 v96, v96
	v_exp_f32_e32 v97, v97
	v_rcp_f32_e32 v94, v94
	v_rcp_f32_e32 v95, v95
	v_add_f32_e32 v96, 1.0, v96
	v_add_f32_e32 v97, 1.0, v97
	v_rcp_f32_e32 v96, v96
	v_rcp_f32_e32 v97, v97
	v_pk_mul_f32 v[88:89], v[88:89], v[94:95]
	v_pk_mul_f32 v[86:87], v[92:93], v[86:87]
	v_pk_mul_f32 v[88:89], v[88:89], v[80:81]
	v_pk_mul_f32 v[80:81], v[90:91], v[96:97]
	v_lshl_add_u64 v[92:93], v[98:99], 0, v[112:113]
	v_pk_mul_f32 v[90:91], v[80:81], v[82:83]
	v_cvt_pk_bf16_f32 v80, v84, v85
	v_cvt_pk_bf16_f32 v81, v86, v87
	v_cvt_pk_bf16_f32 v82, v88, v89
	v_cvt_pk_bf16_f32 v83, v90, v91
	global_store_dwordx4 v[92:93], v[80:83], off nt
	s_nop 1
	v_mul_f32_e32 v80, 0xbfb8aa3b, v76
	v_mul_f32_e32 v81, 0xbfb8aa3b, v77
	v_exp_f32_e32 v80, v80
	v_exp_f32_e32 v81, v81
	v_or_b32_e32 v82, 48, v153
	v_mad_i64_i32 v[82:83], s[16:17], v82, s7, v[138:139]
	v_add_f32_e32 v80, 1.0, v80
	v_add_f32_e32 v81, 1.0, v81
	v_rcp_f32_e32 v80, v80
	v_rcp_f32_e32 v81, v81
	s_nop 0
	v_pk_mul_f32 v[76:77], v[76:77], v[80:81]
	v_mul_f32_e32 v80, 0xbfb8aa3b, v78
	v_mul_f32_e32 v81, 0xbfb8aa3b, v79
	v_exp_f32_e32 v80, v80
; DI unsigned pk2(float lo, float hi) { f32x2 v = {lo, hi}; bf16x2_t b = __builtin_convertvector(v, bf16x2_t); return __builtin_bit_cast(unsigned, b); }
; DI float silu_f(float x) { return x * __builtin_amdgcn_rcpf(1.f + __expf(-x)); }
;     DI void operator()(const pg8::f32x4 (&acc)[2][2][4][2], const pg8::Unit& u, int wr, int wc, int fr, int fq) const {
;     ...
;         for (int ai = 0; ai < 2; ++ai)
; #pragma unroll
;             for (int m = 0; m < 4; ++m) {
;                 bf16* p = H + (size_t)(row0 + ai * 128 + m * 16) * DFF + col;
;                 float h[8];
; #pragma unroll
;                 for (int n = 0; n < 2; ++n)
; #pragma unroll
;                     for (int j = 0; j < 4; ++j) h[n * 4 + j] = silu_f(acc[ai][0][m][n][j]) * acc[ai][1][m][n][j];
;                 u32x4 w; w.x = pk2(h[0], h[1]); w.y = pk2(h[2], h[3]); w.z = pk2(h[4], h[5]); w.w = pk2(h[6], h[7]);
;                 *(u32x4*)p = w;
;                 __builtin_amdgcn_sched_barrier(0);
	v_exp_f32_e32 v81, v81
	v_pk_mul_f32 v[68:69], v[76:77], v[68:69]
	v_add_f32_e32 v76, 1.0, v80
	v_add_f32_e32 v77, 1.0, v81
	v_mul_f32_e32 v80, 0xbfb8aa3b, v72
	v_mul_f32_e32 v81, 0xbfb8aa3b, v73
	v_rcp_f32_e32 v76, v76
	v_rcp_f32_e32 v77, v77
	v_exp_f32_e32 v80, v80
	v_exp_f32_e32 v81, v81
	v_pk_mul_f32 v[76:77], v[78:79], v[76:77]
	v_add_f32_e32 v78, 1.0, v80
	v_add_f32_e32 v79, 1.0, v81
	v_mul_f32_e32 v80, 0xbfb8aa3b, v74
	v_mul_f32_e32 v81, 0xbfb8aa3b, v75
	v_exp_f32_e32 v80, v80
	v_exp_f32_e32 v81, v81
	v_rcp_f32_e32 v78, v78
	v_rcp_f32_e32 v79, v79
	v_add_f32_e32 v80, 1.0, v80
	v_add_f32_e32 v81, 1.0, v81
	v_rcp_f32_e32 v80, v80
	v_rcp_f32_e32 v81, v81
	v_pk_mul_f32 v[72:73], v[72:73], v[78:79]
	v_pk_mul_f32 v[70:71], v[76:77], v[70:71]
	v_pk_mul_f32 v[72:73], v[72:73], v[64:65]
	v_pk_mul_f32 v[64:65], v[74:75], v[80:81]
	v_lshl_add_u64 v[76:77], v[82:83], 0, v[112:113]
	v_pk_mul_f32 v[74:75], v[64:65], v[66:67]
	v_cvt_pk_bf16_f32 v64, v68, v69
	v_cvt_pk_bf16_f32 v65, v70, v71
	v_cvt_pk_bf16_f32 v66, v72, v73
	v_cvt_pk_bf16_f32 v67, v74, v75
	global_store_dwordx4 v[76:77], v[64:67], off nt
	s_nop 1
	v_mul_f32_e32 v64, 0xbfb8aa3b, v60
	v_mul_f32_e32 v65, 0xbfb8aa3b, v61
	v_exp_f32_e32 v64, v64
	v_exp_f32_e32 v65, v65
	v_add_u32_e32 v66, 0x80, v153
	v_mad_i64_i32 v[66:67], s[16:17], v66, s7, v[138:139]
	v_add_f32_e32 v64, 1.0, v64
	v_add_f32_e32 v65, 1.0, v65
	v_rcp_f32_e32 v64, v64
	v_rcp_f32_e32 v65, v65
	s_nop 0
	v_pk_mul_f32 v[60:61], v[60:61], v[64:65]
	v_mul_f32_e32 v64, 0xbfb8aa3b, v62
	v_mul_f32_e32 v65, 0xbfb8aa3b, v63
	v_exp_f32_e32 v64, v64
	v_exp_f32_e32 v65, v65
	v_pk_mul_f32 v[52:53], v[60:61], v[52:53]
	v_add_f32_e32 v60, 1.0, v64
	v_add_f32_e32 v61, 1.0, v65
	v_mul_f32_e32 v64, 0xbfb8aa3b, v56
	v_mul_f32_e32 v65, 0xbfb8aa3b, v57
	v_rcp_f32_e32 v60, v60
	v_rcp_f32_e32 v61, v61
	v_exp_f32_e32 v64, v64
	v_exp_f32_e32 v65, v65
	v_pk_mul_f32 v[60:61], v[62:63], v[60:61]
	v_add_f32_e32 v62, 1.0, v64
	v_add_f32_e32 v63, 1.0, v65
	v_mul_f32_e32 v64, 0xbfb8aa3b, v58
	v_mul_f32_e32 v65, 0xbfb8aa3b, v59
	v_exp_f32_e32 v64, v64
	v_exp_f32_e32 v65, v65
	v_rcp_f32_e32 v62, v62
	v_rcp_f32_e32 v63, v63
	v_add_f32_e32 v64, 1.0, v64
	v_add_f32_e32 v65, 1.0, v65
	v_rcp_f32_e32 v64, v64
	v_rcp_f32_e32 v65, v65
	v_pk_mul_f32 v[56:57], v[56:57], v[62:63]
	v_pk_mul_f32 v[54:55], v[60:61], v[54:55]
	v_pk_mul_f32 v[56:57], v[56:57], v[48:49]
	v_pk_mul_f32 v[48:49], v[58:59], v[64:65]
	v_lshl_add_u64 v[60:61], v[66:67], 0, v[112:113]
	v_pk_mul_f32 v[58:59], v[48:49], v[50:51]
	v_cvt_pk_bf16_f32 v48, v52, v53
	v_cvt_pk_bf16_f32 v49, v54, v55
	v_cvt_pk_bf16_f32 v50, v56, v57
	v_cvt_pk_bf16_f32 v51, v58, v59
	global_store_dwordx4 v[60:61], v[48:51], off nt
	s_nop 1
	v_mul_f32_e32 v48, 0xbfb8aa3b, v44
	v_mul_f32_e32 v49, 0xbfb8aa3b, v45
	v_exp_f32_e32 v48, v48
	v_exp_f32_e32 v49, v49
	v_add_u32_e32 v50, 0x90, v153
	v_mad_i64_i32 v[50:51], s[16:17], v50, s7, v[138:139]
	v_add_f32_e32 v48, 1.0, v48
	v_add_f32_e32 v49, 1.0, v49
	v_rcp_f32_e32 v48, v48
	v_rcp_f32_e32 v49, v49
	s_nop 0
	v_pk_mul_f32 v[44:45], v[44:45], v[48:49]
	v_mul_f32_e32 v48, 0xbfb8aa3b, v46
	v_mul_f32_e32 v49, 0xbfb8aa3b, v47
	v_exp_f32_e32 v48, v48
	v_exp_f32_e32 v49, v49
	v_pk_mul_f32 v[36:37], v[44:45], v[36:37]
	v_add_f32_e32 v44, 1.0, v48
	v_add_f32_e32 v45, 1.0, v49
	v_mul_f32_e32 v48, 0xbfb8aa3b, v40
	v_mul_f32_e32 v49, 0xbfb8aa3b, v41
	v_rcp_f32_e32 v44, v44
	v_rcp_f32_e32 v45, v45
	v_exp_f32_e32 v48, v48
	v_exp_f32_e32 v49, v49
	v_pk_mul_f32 v[44:45], v[46:47], v[44:45]
	v_add_f32_e32 v46, 1.0, v48
	v_add_f32_e32 v47, 1.0, v49
	v_mul_f32_e32 v48, 0xbfb8aa3b, v42
	v_mul_f32_e32 v49, 0xbfb8aa3b, v43
	v_exp_f32_e32 v48, v48
	v_exp_f32_e32 v49, v49
	v_rcp_f32_e32 v46, v46
	v_rcp_f32_e32 v47, v47
	v_add_f32_e32 v48, 1.0, v48
	v_add_f32_e32 v49, 1.0, v49
	v_rcp_f32_e32 v48, v48
; DI unsigned pk2(float lo, float hi) { f32x2 v = {lo, hi}; bf16x2_t b = __builtin_convertvector(v, bf16x2_t); return __builtin_bit_cast(unsigned, b); }
; DI float silu_f(float x) { return x * __builtin_amdgcn_rcpf(1.f + __expf(-x)); }
;     DI void operator()(const pg8::f32x4 (&acc)[2][2][4][2], const pg8::Unit& u, int wr, int wc, int fr, int fq) const {
;     ...
;         for (int ai = 0; ai < 2; ++ai)
; #pragma unroll
;             for (int m = 0; m < 4; ++m) {
;                 bf16* p = H + (size_t)(row0 + ai * 128 + m * 16) * DFF + col;
;                 float h[8];
; #pragma unroll
;                 for (int n = 0; n < 2; ++n)
; #pragma unroll
;                     for (int j = 0; j < 4; ++j) h[n * 4 + j] = silu_f(acc[ai][0][m][n][j]) * acc[ai][1][m][n][j];
;                 u32x4 w; w.x = pk2(h[0], h[1]); w.y = pk2(h[2], h[3]); w.z = pk2(h[4], h[5]); w.w = pk2(h[6], h[7]);
;                 *(u32x4*)p = w;
;                 __builtin_amdgcn_sched_barrier(0);
	v_rcp_f32_e32 v49, v49
	v_pk_mul_f32 v[40:41], v[40:41], v[46:47]
	v_pk_mul_f32 v[38:39], v[44:45], v[38:39]
	v_pk_mul_f32 v[40:41], v[40:41], v[32:33]
	v_pk_mul_f32 v[32:33], v[42:43], v[48:49]
	v_lshl_add_u64 v[44:45], v[50:51], 0, v[112:113]
	v_pk_mul_f32 v[42:43], v[32:33], v[34:35]
	v_cvt_pk_bf16_f32 v32, v36, v37
	v_cvt_pk_bf16_f32 v33, v38, v39
	v_cvt_pk_bf16_f32 v34, v40, v41
	v_cvt_pk_bf16_f32 v35, v42, v43
	global_store_dwordx4 v[44:45], v[32:35], off nt
	s_nop 1
	v_mul_f32_e32 v32, 0xbfb8aa3b, v28
	v_mul_f32_e32 v33, 0xbfb8aa3b, v29
	v_exp_f32_e32 v32, v32
	v_exp_f32_e32 v33, v33
	v_add_u32_e32 v34, 0xa0, v153
	v_mad_i64_i32 v[34:35], s[16:17], v34, s7, v[138:139]
	v_add_f32_e32 v32, 1.0, v32
	v_add_f32_e32 v33, 1.0, v33
	v_rcp_f32_e32 v32, v32
	v_rcp_f32_e32 v33, v33
	s_nop 0
	v_pk_mul_f32 v[28:29], v[28:29], v[32:33]
	v_mul_f32_e32 v32, 0xbfb8aa3b, v30
	v_mul_f32_e32 v33, 0xbfb8aa3b, v31
	v_exp_f32_e32 v32, v32
	v_exp_f32_e32 v33, v33
	v_pk_mul_f32 v[20:21], v[28:29], v[20:21]
	v_add_f32_e32 v28, 1.0, v32
	v_add_f32_e32 v29, 1.0, v33
	v_mul_f32_e32 v32, 0xbfb8aa3b, v24
	v_mul_f32_e32 v33, 0xbfb8aa3b, v25
	v_rcp_f32_e32 v28, v28
	v_rcp_f32_e32 v29, v29
	v_exp_f32_e32 v32, v32
	v_exp_f32_e32 v33, v33
	v_pk_mul_f32 v[28:29], v[30:31], v[28:29]
	v_add_f32_e32 v30, 1.0, v32
	v_add_f32_e32 v31, 1.0, v33
	v_mul_f32_e32 v32, 0xbfb8aa3b, v26
	v_mul_f32_e32 v33, 0xbfb8aa3b, v27
	v_exp_f32_e32 v32, v32
	v_exp_f32_e32 v33, v33
	v_rcp_f32_e32 v30, v30
	v_rcp_f32_e32 v31, v31
	v_add_f32_e32 v32, 1.0, v32
	v_add_f32_e32 v33, 1.0, v33
	v_rcp_f32_e32 v32, v32
	v_rcp_f32_e32 v33, v33
	v_pk_mul_f32 v[24:25], v[24:25], v[30:31]
	v_pk_mul_f32 v[22:23], v[28:29], v[22:23]
	v_pk_mul_f32 v[24:25], v[24:25], v[16:17]
	v_pk_mul_f32 v[16:17], v[26:27], v[32:33]
	v_lshl_add_u64 v[28:29], v[34:35], 0, v[112:113]
	v_pk_mul_f32 v[26:27], v[16:17], v[18:19]
	v_cvt_pk_bf16_f32 v16, v20, v21
	v_cvt_pk_bf16_f32 v17, v22, v23
	v_cvt_pk_bf16_f32 v18, v24, v25
	v_cvt_pk_bf16_f32 v19, v26, v27
	global_store_dwordx4 v[28:29], v[16:19], off nt
	s_nop 1
	v_mul_f32_e32 v18, 0xbfb8aa3b, v12
	v_mul_f32_e32 v19, 0xbfb8aa3b, v13
	v_exp_f32_e32 v18, v18
	v_exp_f32_e32 v19, v19
	v_add_u32_e32 v16, 0xb0, v153
	v_mad_i64_i32 v[16:17], s[16:17], v16, s7, v[138:139]
	v_add_f32_e32 v18, 1.0, v18
	v_add_f32_e32 v19, 1.0, v19
	v_rcp_f32_e32 v18, v18
	v_rcp_f32_e32 v19, v19
	s_nop 0
	v_pk_mul_f32 v[12:13], v[12:13], v[18:19]
	s_nop 0
	v_pk_mul_f32 v[8:9], v[12:13], v[8:9]
	v_mul_f32_e32 v12, 0xbfb8aa3b, v14
	v_mul_f32_e32 v13, 0xbfb8aa3b, v15
	v_exp_f32_e32 v12, v12
	v_exp_f32_e32 v13, v13
	v_add_f32_e32 v12, 1.0, v12
	v_add_f32_e32 v13, 1.0, v13
	v_rcp_f32_e32 v12, v12
	v_rcp_f32_e32 v13, v13
	s_nop 0
	v_pk_mul_f32 v[12:13], v[14:15], v[12:13]
	s_nop 0
	v_pk_mul_f32 v[10:11], v[12:13], v[10:11]
	v_mul_f32_e32 v12, 0xbfb8aa3b, v4
	v_mul_f32_e32 v13, 0xbfb8aa3b, v5
	v_exp_f32_e32 v12, v12
	v_exp_f32_e32 v13, v13
	v_add_f32_e32 v12, 1.0, v12
	v_add_f32_e32 v13, 1.0, v13
	v_rcp_f32_e32 v12, v12
	v_rcp_f32_e32 v13, v13
	s_nop 0
	v_pk_mul_f32 v[4:5], v[4:5], v[12:13]
	s_nop 0
	v_pk_mul_f32 v[4:5], v[4:5], v[0:1]
	v_mul_f32_e32 v0, 0xbfb8aa3b, v6
	v_mul_f32_e32 v1, 0xbfb8aa3b, v7
	v_exp_f32_e32 v0, v0
	v_exp_f32_e32 v1, v1
	v_lshl_add_u64 v[12:13], v[16:17], 0, v[112:113]
	v_add_f32_e32 v0, 1.0, v0
	v_add_f32_e32 v1, 1.0, v1
	v_rcp_f32_e32 v0, v0
	v_rcp_f32_e32 v1, v1
	s_nop 0
	v_pk_mul_f32 v[0:1], v[6:7], v[0:1]
	s_nop 0
	v_pk_mul_f32 v[6:7], v[0:1], v[2:3]
	v_cvt_pk_bf16_f32 v0, v8, v9
	v_cvt_pk_bf16_f32 v1, v10, v11
	v_cvt_pk_bf16_f32 v2, v4, v5
	v_cvt_pk_bf16_f32 v3, v6, v7
	global_store_dwordx4 v[12:13], v[0:3], off nt
	s_andn2_b64 vcc, exec, s[0:1]
	s_mov_b64 s[0:1], -1
	s_cbranch_vccnz .LBB0_917
	s_andn2_b64 vcc, exec, s[2:3]
	s_cbranch_vccnz .LBB0_916
	s_barrier
	s_branch .LBB0_916
